# retention chunk loop software-pipelined: next chunk's K/V/q loads and this chunk's gate loads issued after the second barrier into spare registers (was 5 serialized global round trips per chunk)
# baseline (speedup 1.0000x reference)
; DEVI void ret_item(const Ctx& cx, const float* __restrict__ gn, const float* __restrict__ xfl, const float* __restrict__ g1, const float* __restrict__ winl, int b, int h, unsigned char* lds, int wv) {
;   const int tid = opaque_tid(wv), lane = tid & 63, wave = tid >> 6, idx = lane & 15, quad = lane >> 4;
;   const float lg = log2f(1.f - exp2f(-5.f - (float)h));
;   const int lc = tid & 7, lr = tid >> 3;
;   const int vc = tid & 15, vrw = tid >> 4;
;   f32x4 st[2];
;   st[0] = (f32x4){0.f, 0.f, 0.f, 0.f}; st[1] = (f32x4){0.f, 0.f, 0.f, 0.f};
;   const int et = wave >> 1, dt0 = (wave & 1) * 2;
;   const float cdecay = fexp2(128.f * lg);
;   const int i = wave * 16 + idx;
; #pragma unroll 1
;   for (int ci = 0; ci < 16; ++ci) {
;     const int s0 = ci * 128;
;     u32x4 kr[2], vr[2];
; #pragma unroll
;     for (int r = 0; r < 2; ++r) {
;       kr[r] = *(const u32x4*)(cx.proj + ((size_t)(b * S + s0 + lr + 64 * r)) * PS + C_RK + h * 64 + lc * 8);
;       vr[r] = *(const u32x4*)(cx.retvT + ((size_t)((b * 5 + h) * 64 + vrw + 32 * r)) * S + s0 + vc * 8);
;     }
;     const size_t tokrow = (size_t)(b * S + s0 + i);
;     bf16x8 q[2];
; #pragma unroll
;     for (int ks = 0; ks < 2; ++ks) q[ks] = *(const bf16x8*)(cx.proj + tokrow * PS + C_RQ + h * 64 + ks * 32 + quad * 8);
;     __syncthreads();
; #pragma unroll
;     for (int t = 0; t < 2; ++t)
; #pragma unroll
;       for (int j = 0; j < 4; ++j)
;         *(bf16_t*)(lds + RET_ST + (et * 16 + quad * 4 + j) * LDS_ROW + ((dt0 + t) * 16 + idx) * 2) = f2bf(st[t][j]);
; #pragma unroll
;     for (int r = 0; r < 2; ++r) {
;       const int row = lr + 64 * r;
;       *(u32x4*)(lds + RET_KS + row * LDS_ROW + lc * 16) = kr[r];
;       const float wd = fexp2((float)(127 - row) * lg);
; #pragma unroll
;       for (int e = 0; e < 4; ++e) {
;         unsigned w = kr[r][e];
;         float lo = __uint_as_float(w << 16) * wd, hi = __uint_as_float(w & 0xffff0000u) * wd;
;         *(bf16_t*)(lds + RET_KWT + (lc * 8 + 2 * e) * RET_ROWT + row * 2) = f2bf(lo);
;         *(bf16_t*)(lds + RET_KWT + (lc * 8 + 2 * e + 1) * RET_ROWT + row * 2) = f2bf(hi);
;       }
;       *(u32x4*)(lds + RET_VT + (vrw + 32 * r) * RET_ROWT + vc * 16) = vr[r];
;     }
;     __syncthreads();
;     bf16x8 pb[4];
; #pragma unroll
;     for (int kc = 0; kc < 4; ++kc) {
;       f32x4 s2[2];
; #pragma unroll
;       for (int u = 0; u < 2; ++u) {
.LBB0_1294:
	s_mul_hi_i32 s0, s8, 0x66666667
	s_lshr_b32 s1, s0, 31
	s_ashr_i32 s0, s0, 1
	s_add_i32 s3, s0, s1
	s_mul_i32 s0, s3, 5
	s_sub_i32 s4, s8, s0
	v_cvt_f32_i32_e32 v0, s4
	v_readlane_b32 s0, v252, 46
	v_mbcnt_lo_u32_b32 v5, -1, 0
	v_mbcnt_hi_u32_b32 v5, -1, v5
	v_mov_b32_e32 v2, 0x42800000
	v_sub_f32_e32 v0, 0xc0a00000, v0
	v_add_u32_e32 v1, s0, v5
	s_mov_b32 s0, 0xc2fc0000
	v_cmp_gt_f32_e32 vcc, s0, v0
	s_and_b64 s[0:1], vcc, exec
	s_cselect_b32 s0, 0xffffffc0, 0
	v_cndmask_b32_e32 v2, 0, v2, vcc
	v_add_f32_e32 v0, v0, v2
	v_exp_f32_e32 v0, v0
	v_ashrrev_i32_e32 v20, 3, v1
	v_and_b32_e32 v19, 15, v5
	v_bfe_u32 v3, v5, 4, 2
	v_ldexp_f32 v0, v0, s0
	v_sub_f32_e32 v0, 1.0, v0
	v_cmp_gt_f32_e32 vcc, s77, v0
	s_and_b64 s[0:1], vcc, exec
	s_cselect_b32 s0, 32, 0
	v_ldexp_f32 v0, v0, s0
	v_and_b32_e32 v6, 7, v5
	v_bfi_b32 v8, -16, v20, v5
	v_lshlrev_b32_e32 v5, 2, v5
	v_log_f32_e32 v0, v0
	v_bitop3_b32 v131, v5, s58, v237 bitop3:0x6c
	v_sub_u32_e32 v5, 0x7f, v20
	v_cvt_f32_i32_e32 v5, v5
	v_mov_b32_e32 v2, 0x42000000
	v_cndmask_b32_e32 v2, 0, v2, vcc
	v_sub_f32_e32 v23, v0, v2
	v_mul_f32_e32 v5, v23, v5
	v_exp_f32_e32 v152, v5
	v_sub_u32_e32 v5, 63, v20
	v_cvt_f32_i32_e32 v5, v5
	v_ashrrev_i32_e32 v13, 6, v1
	v_lshlrev_b32_e32 v0, 1, v13
	s_waitcnt vmcnt(9)
	v_and_b32_e32 v24, 2, v0
	v_mul_f32_e32 v0, 0x43000000, v23
	v_lshlrev_b32_e32 v25, 4, v13
	v_ashrrev_i32_e32 v14, 4, v1
	v_exp_f32_e32 v76, v0
	v_or_b32_e32 v1, v25, v19
	v_lshlrev_b32_e32 v0, 2, v3
	v_mul_f32_e32 v5, v23, v5
	v_exp_f32_e32 v155, v5
	v_sub_u32_e32 v5, v1, v0
	v_cvt_f32_i32_e32 v5, v5
	s_lshl_b32 s74, s4, 6
	s_ashr_i32 s75, s74, 31
	s_lshl_b32 s3, s3, 11
	v_mul_f32_e32 v5, v23, v5
	v_exp_f32_e32 v156, v5
	v_xad_u32 v5, v0, -1, v1
	v_cvt_f32_i32_e32 v5, v5
	s_lshl_b64 s[0:1], s[74:75], 2
	v_readlane_b32 s5, v255, 15
	v_and_b32_e32 v4, -16, v20
	s_add_u32 s76, s5, s0
	v_readlane_b32 s0, v255, 19
	v_mul_f32_e32 v5, v23, v5
	v_or_b32_e32 v16, v4, v0
	s_addc_u32 s77, s0, s1
	s_movk_i32 s0, 0x90
	v_exp_f32_e32 v157, v5
	v_or_b32_e32 v5, 3, v0
	v_mul_lo_u32 v22, v16, s0
	v_sub_u32_e32 v16, v1, v5
	v_cvt_f32_i32_e32 v16, v16
	v_lshl_add_u32 v10, s8, 6, v14
	v_cmp_lt_i32_e64 s[8:9], v1, v5
	s_waitcnt vmcnt(8)
	v_mul_lo_u32 v28, v20, s0
	v_mul_f32_e32 v5, v23, v16
	v_exp_f32_e32 v85, v5
	v_or_b32_e32 v5, 17, v0
	s_movk_i32 s0, 0x880
	v_cmp_lt_i32_e64 s[14:15], v1, v5
	v_sub_u32_e32 v5, v1, v5
	v_lshlrev_b32_e32 v12, 4, v6
	s_movk_i32 s4, 0x110
	v_mad_u32_u24 v154, v6, s0, 0
	v_or_b32_e32 v6, 2, v0
	v_cvt_f32_i32_e32 v5, v5
	v_mul_lo_u32 v29, v14, s4
	v_sub_u32_e32 v14, v1, v6
	v_cvt_f32_i32_e32 v14, v14
	v_mul_f32_e32 v5, v23, v5
	v_exp_f32_e32 v87, v5
	v_or_b32_e32 v5, 19, v0
	v_mul_f32_e32 v14, v23, v14
	v_cmp_lt_i32_e64 s[10:11], v1, v6
	v_or_b32_e32 v6, 16, v0
	v_sub_u32_e32 v32, v1, v5
	v_exp_f32_e32 v84, v14
	v_sub_u32_e32 v14, v1, v6
	v_cvt_f32_i32_e32 v32, v32
	v_cvt_f32_i32_e32 v14, v14
	v_cmp_lt_i32_e64 s[18:19], v1, v5
	v_add_u32_e32 v4, 1, v1
	v_mul_f32_e32 v5, v23, v32
	v_mul_f32_e32 v14, v23, v14
	v_exp_f32_e32 v89, v5
	v_or_b32_e32 v5, 33, v0
	v_exp_f32_e32 v86, v14
	v_or_b32_e32 v14, 18, v0
	v_cmp_lt_i32_e64 s[24:25], v1, v5
	v_sub_u32_e32 v5, v1, v5
	v_sub_u32_e32 v16, v1, v14
	v_cvt_f32_i32_e32 v5, v5
	v_cvt_f32_i32_e32 v16, v16
	v_cmp_lt_i32_e64 s[20:21], v1, v14
	v_or_b32_e32 v14, 32, v0
	v_mul_f32_e32 v5, v23, v5
	v_mul_f32_e32 v16, v23, v16
	v_exp_f32_e32 v91, v5
	v_or_b32_e32 v5, 35, v0
	v_exp_f32_e32 v88, v16
	v_sub_u32_e32 v16, v1, v14
	v_sub_u32_e32 v34, v1, v5
	v_cvt_f32_i32_e32 v16, v16
	v_cvt_f32_i32_e32 v34, v34
	v_cmp_lt_i32_e64 s[28:29], v1, v5
	v_cvt_f32_i32_e32 v4, v4
	v_mul_f32_e32 v16, v23, v16
	v_mul_f32_e32 v5, v23, v34
	v_exp_f32_e32 v90, v16
	v_or_b32_e32 v16, 34, v0
	v_exp_f32_e32 v93, v5
	v_or_b32_e32 v5, 49, v0
	v_sub_u32_e32 v32, v1, v16
	v_cmp_lt_i32_e64 s[36:37], v1, v5
	v_sub_u32_e32 v5, v1, v5
	v_cvt_f32_i32_e32 v32, v32
	v_cvt_f32_i32_e32 v5, v5
	v_cmp_lt_i32_e64 s[30:31], v1, v16
	v_or_b32_e32 v16, 48, v0
	v_mul_f32_e32 v32, v23, v32
	v_mul_f32_e32 v5, v23, v5
	v_exp_f32_e32 v92, v32
	v_sub_u32_e32 v32, v1, v16
	v_exp_f32_e32 v95, v5
	v_or_b32_e32 v5, 51, v0
	v_cvt_f32_i32_e32 v32, v32
	v_sub_u32_e32 v35, v1, v5
	v_cvt_f32_i32_e32 v35, v35
	v_cmp_lt_i32_e64 s[40:41], v1, v5
	v_mul_f32_e32 v32, v23, v32
	v_exp_f32_e32 v94, v32
	v_or_b32_e32 v32, 50, v0
	v_mul_f32_e32 v5, v23, v35
	v_sub_u32_e32 v34, v1, v32
	v_exp_f32_e32 v97, v5
	v_or_b32_e32 v5, 0x41, v0
	v_cvt_f32_i32_e32 v34, v34
	v_cmp_lt_i32_e64 s[46:47], v1, v5
	v_sub_u32_e32 v5, v1, v5
	v_cvt_f32_i32_e32 v5, v5
	v_mul_f32_e32 v34, v23, v34
	v_cmp_lt_i32_e64 s[42:43], v1, v32
	v_or_b32_e32 v32, 64, v0
	v_exp_f32_e32 v96, v34
	v_sub_u32_e32 v34, v1, v32
	v_mul_f32_e32 v5, v23, v5
	v_cvt_f32_i32_e32 v34, v34
	v_exp_f32_e32 v99, v5
	v_or_b32_e32 v5, 0x43, v0
	v_sub_u32_e32 v35, v1, v5
	v_cvt_f32_i32_e32 v35, v35
	v_mul_f32_e32 v34, v23, v34
	v_cmp_lt_i32_e64 s[48:49], v1, v32
	v_or_b32_e32 v32, 0x42, v0
	v_exp_f32_e32 v98, v34
	v_sub_u32_e32 v34, v1, v32
	v_cvt_f32_i32_e32 v34, v34
	v_cmp_lt_i32_e64 s[50:51], v1, v5
	v_mul_f32_e32 v5, v23, v35
	v_exp_f32_e32 v101, v5
	v_or_b32_e32 v5, 0x51, v0
	v_cmp_lt_i32_e64 s[56:57], v1, v5
	v_sub_u32_e32 v5, v1, v5
	v_cvt_f32_i32_e32 v5, v5
	v_mul_f32_e32 v34, v23, v34
	v_cmp_lt_i32_e64 s[52:53], v1, v32
	v_or_b32_e32 v32, 0x50, v0
	v_exp_f32_e32 v100, v34
	v_sub_u32_e32 v34, v1, v32
	v_cvt_f32_i32_e32 v34, v34
	v_mul_f32_e32 v5, v23, v5
	v_exp_f32_e32 v103, v5
	v_or_b32_e32 v5, 0x53, v0
	v_sub_u32_e32 v35, v1, v5
	v_mul_f32_e32 v34, v23, v34
	v_cmp_lt_i32_e64 s[58:59], v1, v32
	v_or_b32_e32 v32, 0x52, v0
	v_cvt_f32_i32_e32 v35, v35
; DEVI float fexp2(float x) { return __builtin_amdgcn_exp2f(x); }
; DEVI void ret_item(const Ctx& cx, const float* __restrict__ gn, const float* __restrict__ xfl, const float* __restrict__ g1, const float* __restrict__ winl, int b, int h, unsigned char* lds, int wv) {
;     ...
;   const int vc = tid & 15, vrw = tid >> 4;
;   f32x4 st[2];
;   st[0] = (f32x4){0.f, 0.f, 0.f, 0.f}; st[1] = (f32x4){0.f, 0.f, 0.f, 0.f};
;   const int et = wave >> 1, dt0 = (wave & 1) * 2;
;   const float cdecay = fexp2(128.f * lg);
;   const int i = wave * 16 + idx;
; #pragma unroll 1
;   for (int ci = 0; ci < 16; ++ci) {
;     const int s0 = ci * 128;
;     u32x4 kr[2], vr[2];
; #pragma unroll
;     for (int r = 0; r < 2; ++r) {
;       kr[r] = *(const u32x4*)(cx.proj + ((size_t)(b * S + s0 + lr + 64 * r)) * PS + C_RK + h * 64 + lc * 8);
;       vr[r] = *(const u32x4*)(cx.retvT + ((size_t)((b * 5 + h) * 64 + vrw + 32 * r)) * S + s0 + vc * 8);
;     }
;     const size_t tokrow = (size_t)(b * S + s0 + i);
;     bf16x8 q[2];
; #pragma unroll
;     for (int ks = 0; ks < 2; ++ks) q[ks] = *(const bf16x8*)(cx.proj + tokrow * PS + C_RQ + h * 64 + ks * 32 + quad * 8);
	v_exp_f32_e32 v102, v34
	v_sub_u32_e32 v34, v1, v32
	v_cvt_f32_i32_e32 v34, v34
	v_cmp_lt_i32_e64 s[60:61], v1, v5
	v_mul_f32_e32 v5, v23, v35
	v_exp_f32_e32 v105, v5
	v_or_b32_e32 v5, 0x61, v0
	v_mul_f32_e32 v34, v23, v34
	v_cmp_lt_i32_e64 s[62:63], v1, v32
	v_or_b32_e32 v32, 0x60, v0
	v_cmp_lt_i32_e64 s[66:67], v1, v5
	v_sub_u32_e32 v5, v1, v5
	v_exp_f32_e32 v104, v34
	v_sub_u32_e32 v34, v1, v32
	v_cvt_f32_i32_e32 v5, v5
	v_cvt_f32_i32_e32 v34, v34
	v_cmp_lt_i32_e64 s[68:69], v1, v32
	v_or_b32_e32 v32, 0x62, v0
	v_mul_f32_e32 v5, v23, v5
	v_mul_f32_e32 v34, v23, v34
	v_exp_f32_e32 v107, v5
	v_or_b32_e32 v5, 0x63, v0
	v_exp_f32_e32 v106, v34
	v_sub_u32_e32 v34, v1, v32
	v_sub_u32_e32 v35, v1, v5
	v_cvt_f32_i32_e32 v34, v34
	v_cvt_f32_i32_e32 v35, v35
	v_cmp_lt_i32_e64 s[70:71], v1, v5
	v_cmp_lt_i32_e64 s[72:73], v1, v32
	v_mul_f32_e32 v34, v23, v34
	v_mul_f32_e32 v5, v23, v35
	v_or_b32_e32 v35, 0x70, v0
	v_exp_f32_e32 v108, v34
	v_exp_f32_e32 v109, v5
	v_or_b32_e32 v34, 0x71, v0
	v_sub_u32_e32 v5, v1, v35
	v_lshlrev_b32_e32 v32, 2, v6
	v_mul_f32_e32 v4, v23, v4
	v_cvt_f32_i32_e32 v36, v5
	v_sub_u32_e32 v5, v1, v34
	v_lshl_add_u64 v[112:113], s[76:77], 0, v[32:33]
	v_lshlrev_b32_e32 v32, 2, v14
	v_exp_f32_e32 v78, v4
	v_lshlrev_b32_e32 v4, 4, v3
	v_cvt_f32_i32_e32 v37, v5
	v_mov_b32_e32 v5, v33
	v_lshl_add_u64 v[114:115], s[76:77], 0, v[32:33]
	v_lshlrev_b32_e32 v32, 2, v16
	v_lshl_add_u64 v[110:111], s[76:77], 0, v[4:5]
	v_lshl_add_u64 v[116:117], s[76:77], 0, v[32:33]
	v_readlane_b32 s76, v252, 40
	s_lshl_b64 s[74:75], s[74:75], 1
	v_readlane_b32 s78, v252, 42
	v_readlane_b32 s77, v252, 41
	v_readlane_b32 s79, v252, 43
	s_add_u32 s84, s78, s74
	s_addc_u32 s85, s79, s75
	v_readlane_b32 s76, v254, 14
	v_mul_f32_e32 v5, v23, v36
	v_readlane_b32 s77, v254, 15
	s_add_u32 s86, s76, s74
	v_exp_f32_e32 v118, v5
	v_mul_f32_e32 v5, v23, v37
	v_or_b32_e32 v37, 0x72, v0
	v_cmp_lt_i32_e64 s[0:1], -1, v13
	v_cmp_lt_i32_e64 s[12:13], 0, v13
	v_cmp_lt_i32_e64 s[22:23], 1, v13
	v_cmp_lt_i32_e64 s[34:35], 2, v13
	v_cmp_lt_i32_e64 s[44:45], 3, v13
	v_cmp_lt_i32_e64 s[54:55], 4, v13
	v_cmp_lt_i32_e64 s[64:65], 5, v13
	s_addc_u32 s87, s77, s75
	v_cmp_lt_i32_e64 s[74:75], 6, v13
	v_or_b32_e32 v36, 0x73, v0
	v_sub_u32_e32 v13, v1, v37
	v_cvt_f32_i32_e32 v13, v13
	v_sub_u32_e32 v32, v1, v36
	v_cvt_f32_i32_e32 v32, v32
	v_exp_f32_e32 v119, v5
	v_mul_f32_e32 v5, v23, v13
	v_or_b32_e32 v13, 16, v19
	v_lshl_add_u32 v26, v19, 1, 0
	v_or_b32_e32 v27, 1, v24
	v_exp_f32_e32 v120, v5
	v_mul_f32_e32 v5, v23, v32
	v_mul_u32_u24_e32 v23, 0x90, v13
	v_lshl_or_b32 v13, v24, 4, v19
	v_mul_lo_u32 v8, v8, s4
	v_ashrrev_i32_e32 v11, 31, v10
	v_lshl_add_u32 v21, v24, 5, v26
	v_mul_u32_u24_e32 v24, 0x110, v13
	v_lshl_or_b32 v13, v27, 4, v19
	v_mad_u32_u24 v17, v19, 14, v26
	v_add_u32_e32 v18, 0, v8
	v_lshlrev_b64 v[8:9], 12, v[10:11]
	v_add_u32_e32 v10, 32, v10
	v_lshl_add_u32 v26, v27, 5, v26
	v_mul_u32_u24_e32 v27, 0x110, v13
	v_mov_b32_e32 v13, v33
	v_add_u32_e32 v15, 0, v12
	v_ashrrev_i32_e32 v11, 31, v10
	v_exp_f32_e32 v121, v5
	v_lshl_add_u64 v[122:123], s[84:85], 0, v[12:13]
	v_add_u32_e32 v12, s3, v25
	v_lshlrev_b32_e32 v2, 3, v3
	v_add_u32_e32 v3, 0, v4
	v_lshlrev_b64 v[10:11], 12, v[10:11]
	v_lshlrev_b32_e32 v153, 1, v20
	v_or_b32_e32 v158, v12, v19
	v_lshlrev_b32_e32 v12, 4, v19
	v_readlane_b32 s76, v253, 30
	v_mov_b32_e32 v74, 0
	v_sub_u32_e32 v7, v3, v2
	v_add_u32_e32 v30, 0x80, v153
	v_mul_u32_u24_e32 v31, 0x90, v19
	v_mul_u32_u24_e32 v5, 0x110, v19
	v_or_b32_e32 v8, v8, v12
	v_readlane_b32 s77, v253, 31
	v_or_b32_e32 v10, v10, v12
	s_mov_b32 s92, 0x800000
	s_mov_b32 s2, 0
	v_mov_b32_e32 v79, v78
	v_mov_b32_e32 v80, v78
	v_mov_b32_e32 v81, v78
	v_mov_b32_e32 v82, v76
	v_mov_b32_e32 v83, v76
	v_cmp_lt_i32_e64 s[4:5], v1, v0
	v_cmp_gt_i32_e64 s[6:7], v1, v0
	v_cmp_lt_i32_e64 s[16:17], v1, v6
	v_cmp_lt_i32_e64 s[26:27], v1, v14
	v_cmp_lt_i32_e64 s[38:39], v1, v16
	v_lshl_add_u64 v[124:125], s[76:77], 0, v[8:9]
	v_lshl_add_u64 v[126:127], s[76:77], 0, v[10:11]
	v_add_u32_e32 v159, s3, v20
	v_lshlrev_b32_e32 v32, 1, v2
	v_add_u32_e32 v160, v21, v22
	v_add_u32_e32 v161, v26, v22
	v_add_u32_e32 v162, v15, v28
	v_add_u32_e32 v163, v17, v29
	v_add_u32_e32 v164, v154, v30
	v_add_u32_e32 v165, v18, v4
	v_add_u32_e32 v166, v3, v24
	v_add_u32_e32 v167, v3, v27
	v_lshlrev_b32_e32 v128, 1, v0
	v_lshlrev_b32_e32 v136, 1, v6
	v_lshlrev_b32_e32 v138, 1, v14
	v_lshlrev_b32_e32 v140, 1, v16
	v_add_u32_e32 v168, v3, v31
	v_add_u32_e32 v169, v7, v5
	v_add_u32_e32 v170, v3, v23
	v_mov_b32_e32 v75, v74
	v_mov_b32_e32 v142, v74
	v_mov_b32_e32 v143, v74
	v_mov_b32_e32 v144, v74
	v_mov_b32_e32 v145, v74
	v_mov_b32_e32 v146, v74
	v_mov_b32_e32 v147, v74
	v_cmp_lt_i32_e64 s[76:77], v1, v34
	v_cmp_lt_i32_e64 s[78:79], v1, v35
	v_cmp_lt_i32_e64 s[80:81], v1, v36
	v_cmp_lt_i32_e64 s[82:83], v1, v37
	v_add_u32_e32 v202, s2, v159
	v_mul_u32_u24_e32 v202, 0x1200, v202
	v_add_co_u32_e32 v204, vcc, v122, v202
	v_addc_co_u32_e32 v205, vcc, 0, v123, vcc
	global_load_dwordx4 v[178:181], v[204:205], off offset:3328
	global_load_dwordx4 v[182:185], v[124:125], off
	v_add_co_u32_e32 v206, vcc, 0x48000, v204
	v_addc_co_u32_e32 v207, vcc, 0, v205, vcc
	global_load_dwordx4 v[186:189], v[206:207], off offset:3328
	global_load_dwordx4 v[190:193], v[126:127], off
	v_add_u32_e32 v202, s2, v158
	v_mul_u32_u24_e32 v202, 0x1200, v202
	v_mov_b32_e32 v208, s84
	v_mov_b32_e32 v209, s85
	v_add_co_u32_e32 v208, vcc, v208, v202
	v_addc_co_u32_e32 v209, vcc, 0, v209, vcc
	v_add_co_u32_e32 v208, vcc, v208, v32
	v_addc_co_u32_e32 v209, vcc, 0, v209, vcc
	global_load_dwordx4 v[194:197], v[208:209], off offset:2688
	global_load_dwordx4 v[198:201], v[208:209], off offset:2752
	s_waitcnt vmcnt(0)
	s_branch .LBB0_1296
; DEVI f32x4 mfma16(bf16x8 a, bf16x8 b, f32x4 c) { return __builtin_amdgcn_mfma_f32_16x16x32_bf16(a, b, c, 0, 0, 0); }
; DEVI float fexp2(float x) { return __builtin_amdgcn_exp2f(x); }
; template <int M> DEVI float shx(float v) { return __int_as_float(__builtin_amdgcn_ds_swizzle(__float_as_int(v), (M << 10) | 0x1f)); }
; DEVI float shx32(float v, int lane) { return __int_as_float(__builtin_amdgcn_ds_bpermute((lane ^ 32) << 2, __float_as_int(v))); }
; DEVI void ret_item(const Ctx& cx, const float* __restrict__ gn, const float* __restrict__ xfl, const float* __restrict__ g1, const float* __restrict__ winl, int b, int h, unsigned char* lds, int wv) {
;     ...
;       for (int ks = 0; ks < 2; ++ks) {
;         bf16x8 sf = *(const bf16x8*)(lds + RET_ST + (dvt * 16 + idx) * LDS_ROW + ks * 64 + quad * 16);
;         oi[dvt] = mfma16(sf, q[ks], oi[dvt]);
;       }
;     }
;     const float rd = fexp2((float)(i + 1) * lg);
; #pragma unroll
;     for (int dvt = 0; dvt < 4; ++dvt) o[dvt] += oi[dvt] * rd;
; #pragma unroll
;     for (int t = 0; t < 2; ++t) {
;       f32x4 nw = (f32x4){0.f, 0.f, 0.f, 0.f};
; #pragma unroll
;       for (int kc = 0; kc < 4; ++kc) {
;         bf16x8 vf = *(const bf16x8*)(lds + RET_VT + (et * 16 + idx) * RET_ROWT + kc * 64 + quad * 16);
;         bf16x8 kf = *(const bf16x8*)(lds + RET_KWT + ((dt0 + t) * 16 + idx) * RET_ROWT + kc * 64 + quad * 16);
;         nw = mfma16(vf, kf, nw);
;       }
;       st[t] = st[t] * cdecay + nw;
;     }
;     float sum = 0.f;
; #pragma unroll
;     for (int dvt = 0; dvt < 4; ++dvt) sum += o[dvt][0] + o[dvt][1] + o[dvt][2] + o[dvt][3];
;     sum += shx<16>(sum); sum += shx32(sum, quad * 16 + idx);
;     const float mu = sum * (1.f / 64.f);
;     float var = 0.f;
; #pragma unroll
;     for (int dvt = 0; dvt < 4; ++dvt)
; #pragma unroll
;       for (int j = 0; j < 4; ++j) { float d = o[dvt][j] - mu; var += d * d; }
;     var += shx<16>(var); var += shx32(var, quad * 16 + idx);
;     const float rstd = rsqrtf(var * (1.f / 64.f) + 1e-6f);
; #pragma unroll
;     for (int dvt = 0; dvt < 4; ++dvt) {
;       const int dv = dvt * 16 + quad * 4;
;       const u32x2 gw = *(const u32x2*)(cx.proj + tokrow * PS + C_RG + h * 64 + dv);
.LBB0_1295:
	s_or_b64 exec, exec, vcc
	ds_read_b128 v[0:3], v170 offset:57856
	ds_read_b128 v[4:7], v170 offset:57920
	v_pk_fma_f32 v[8:9], v[80:81], v[60:61], v[18:19]
	v_pk_fma_f32 v[18:19], v[78:79], v[58:59], v[16:17]
	v_pk_fma_f32 v[10:11], v[80:81], v[64:65], v[22:23]
	v_pk_fma_f32 v[16:17], v[78:79], v[62:63], v[20:21]
	v_mov_b32_e32 v77, v76
	v_mov_b32_e32 v129, v33
	v_ashrrev_i32_e32 v151, 31, v150
	s_waitcnt lgkmcnt(1)
	v_mfma_f32_16x16x32_bf16 v[0:3], v[0:3], v[38:41], 0
	v_mov_b32_e32 v137, v33
	v_mov_b32_e32 v139, v33
	v_mov_b32_e32 v141, v33
	s_waitcnt lgkmcnt(0)
	v_mfma_f32_16x16x32_bf16 v[0:3], v[4:7], v[34:37], v[0:3]
	v_fma_f32 v34, v80, v68, v26
	v_fma_f32 v35, v81, v69, v27
	v_pk_fma_f32 v[36:37], v[78:79], v[66:67], v[24:25]
	s_addk_i32 s2, 0x80
	s_cmpk_lg_i32 s2, 0x800
	s_nop 2
	v_pk_fma_f32 v[38:39], v[80:81], v[2:3], v[30:31]
	v_pk_fma_f32 v[40:41], v[78:79], v[0:1], v[28:29]
	ds_read_b128 v[0:3], v165 offset:35840
	ds_read_b128 v[4:7], v166 offset:18432
	ds_read_b128 v[12:15], v165 offset:35904
	ds_read_b128 v[20:23], v166 offset:18496
	s_waitcnt lgkmcnt(2)
	v_mfma_f32_16x16x32_bf16 v[4:7], v[0:3], v[4:7], 0
	s_waitcnt lgkmcnt(0)
	v_mfma_f32_16x16x32_bf16 v[4:7], v[12:15], v[20:23], v[4:7]
	ds_read_b128 v[20:23], v165 offset:35968
	ds_read_b128 v[24:27], v166 offset:18560
	s_waitcnt lgkmcnt(0)
	v_mfma_f32_16x16x32_bf16 v[4:7], v[20:23], v[24:27], v[4:7]
	ds_read_b128 v[24:27], v165 offset:36032
	ds_read_b128 v[28:31], v166 offset:18624
	s_waitcnt lgkmcnt(0)
	v_mfma_f32_16x16x32_bf16 v[4:7], v[24:27], v[28:31], v[4:7]
	s_nop 7
	v_pk_fma_f32 v[142:143], v[76:77], v[142:143], v[6:7]
	v_pk_fma_f32 v[74:75], v[82:83], v[74:75], v[4:5]
	ds_read_b128 v[4:7], v167 offset:18432
	s_waitcnt lgkmcnt(0)
	v_mfma_f32_16x16x32_bf16 v[0:3], v[0:3], v[4:7], 0
	ds_read_b128 v[4:7], v167 offset:18496
	s_waitcnt lgkmcnt(0)
	v_mfma_f32_16x16x32_bf16 v[0:3], v[12:15], v[4:7], v[0:3]
	ds_read_b128 v[4:7], v167 offset:18560
	s_waitcnt lgkmcnt(0)
	v_mfma_f32_16x16x32_bf16 v[0:3], v[20:23], v[4:7], v[0:3]
	ds_read_b128 v[4:7], v167 offset:18624
	v_lshlrev_b64 v[20:21], 11, v[150:151]
	s_waitcnt lgkmcnt(0)
	v_mfma_f32_16x16x32_bf16 v[0:3], v[24:27], v[4:7], v[0:3]
	s_nop 7
	v_pk_fma_f32 v[146:147], v[76:77], v[146:147], v[2:3]
	v_pk_fma_f32 v[144:145], v[82:83], v[144:145], v[0:1]
	v_mov_b32_e32 v0, v16
	v_mov_b32_e32 v1, v18
	v_mov_b32_e32 v2, v17
	v_mov_b32_e32 v3, v19
	v_pk_add_f32 v[0:1], v[0:1], v[2:3]
	v_mov_b32_e32 v2, v10
	v_mov_b32_e32 v3, v8
	v_pk_add_f32 v[0:1], v[2:3], v[0:1]
	v_mov_b32_e32 v2, v11
	v_mov_b32_e32 v3, v9
	v_pk_add_f32 v[0:1], v[2:3], v[0:1]
	v_mov_b32_e32 v2, v37
	v_add_f32_e32 v1, 0, v1
	v_add_f32_e32 v4, v0, v1
	v_mov_b32_e32 v0, v36
	v_mov_b32_e32 v1, v40
	v_mov_b32_e32 v3, v41
	v_pk_add_f32 v[0:1], v[0:1], v[2:3]
	v_mov_b32_e32 v2, v34
	v_mov_b32_e32 v3, v38
	v_pk_add_f32 v[0:1], v[2:3], v[0:1]
	v_mov_b32_e32 v2, v35
	v_mov_b32_e32 v3, v39
	v_pk_add_f32 v[0:1], v[2:3], v[0:1]
	s_nop 0
	v_add_f32_e32 v0, v0, v4
	v_add_f32_e32 v0, v0, v1
	ds_swizzle_b32 v1, v0 offset:swizzle(SWAP,16)
	s_waitcnt lgkmcnt(0)
	v_add_f32_e32 v0, v0, v1
	ds_bpermute_b32 v1, v131, v0
	s_waitcnt lgkmcnt(0)
	v_add_f32_e32 v1, v0, v1
	v_fmac_f32_e32 v19, 0xbc800000, v1
	v_fmamk_f32 v18, v1, 0xbc800000, v18
	v_mul_f32_e32 v4, v19, v19
	v_fmac_f32_e32 v4, v18, v18
	v_fmamk_f32 v8, v1, 0xbc800000, v8
	v_fmac_f32_e32 v4, v8, v8
	v_fmac_f32_e32 v9, 0xbc800000, v1
	v_fmac_f32_e32 v4, v9, v9
	v_fmamk_f32 v22, v1, 0xbc800000, v16
	v_fmac_f32_e32 v4, v22, v22
	v_fmac_f32_e32 v17, 0xbc800000, v1
	v_mul_f32_e32 v0, 0x3c800000, v1
	v_fmac_f32_e32 v4, v17, v17
	v_fmamk_f32 v10, v1, 0xbc800000, v10
	v_fmac_f32_e32 v4, v10, v10
	v_fmac_f32_e32 v11, 0xbc800000, v1
	v_pk_add_f32 v[14:15], v[36:37], v[0:1] op_sel_hi:[1,0] neg_lo:[0,1] neg_hi:[0,1]
	v_fmac_f32_e32 v4, v11, v11
	v_pk_mul_f32 v[2:3], v[14:15], v[14:15]
	s_nop 0
	v_add_f32_e32 v1, v2, v4
	v_add_f32_e32 v1, v3, v1
	v_pk_add_f32 v[12:13], v[34:35], v[0:1] op_sel_hi:[1,0] neg_lo:[0,1] neg_hi:[0,1]
	s_nop 0
	v_pk_mul_f32 v[2:3], v[12:13], v[12:13]
	s_nop 0
	v_add_f32_e32 v1, v2, v1
	v_add_f32_e32 v1, v3, v1
	v_pk_add_f32 v[6:7], v[40:41], v[0:1] op_sel_hi:[1,0] neg_lo:[0,1] neg_hi:[0,1]
	s_nop 0
	v_pk_mul_f32 v[2:3], v[6:7], v[6:7]
	s_nop 0
	v_add_f32_e32 v1, v2, v1
	v_pk_add_f32 v[4:5], v[38:39], v[0:1] op_sel_hi:[1,0] neg_lo:[0,1] neg_hi:[0,1]
	v_add_f32_e32 v2, v3, v1
	v_pk_mul_f32 v[0:1], v[4:5], v[4:5]
	s_nop 0
	v_add_f32_e32 v0, v0, v2
	v_add_f32_e32 v0, v1, v0
	ds_swizzle_b32 v1, v0 offset:swizzle(SWAP,16)
	s_waitcnt lgkmcnt(0)
	v_add_f32_e32 v0, v0, v1
	ds_bpermute_b32 v1, v131, v0
	s_waitcnt lgkmcnt(0)
	v_add_f32_e32 v0, v0, v1
	v_fmamk_f32 v0, v0, 0x3c800000, v224
	v_cmp_gt_f32_e32 vcc, s92, v0
	v_mul_f32_e32 v1, 0x4b800000, v0
	s_nop 0
	v_cndmask_b32_e32 v0, v0, v1, vcc
	v_rsq_f32_e32 v0, v0
	s_nop 0
	v_mul_f32_e32 v1, 0x45800000, v0
	v_cndmask_b32_e32 v16, v0, v1, vcc
	v_lshl_add_u64 v[0:1], v[148:149], 0, v[128:129]
	s_waitcnt vmcnt(6)
; DEVI void store_bf4(bf16_t* p, f32x4 v) { u32x2 w; w.x = pk2(v[0], v[1]); w.y = pk2(v[2], v[3]); *(u32x2*)p = w; }
; DEVI float sigmoidf(float x) { return 1.f / (1.f + __expf(-x)); }
; DEVI void ret_item(const Ctx& cx, const float* __restrict__ gn, const float* __restrict__ xfl, const float* __restrict__ g1, const float* __restrict__ winl, int b, int h, unsigned char* lds, int wv) {
;     ...
;     for (int dvt = 0; dvt < 4; ++dvt) {
;       const int dv = dvt * 16 + quad * 4;
;       const u32x2 gw = *(const u32x2*)(cx.proj + tokrow * PS + C_RG + h * 64 + dv);
;       const float4 gg = *(const float4*)(gn + h * 64 + dv);
;       float gt[4] = {__uint_as_float(gw.x << 16), __uint_as_float(gw.x & 0xffff0000u), __uint_as_float(gw.y << 16), __uint_as_float(gw.y & 0xffff0000u)};
;       float gnv[4] = {gg.x, gg.y, gg.z, gg.w};
;       f32x4 r;
; #pragma unroll
;       for (int j = 0; j < 4; ++j) r[j] = (o[dvt][j] - mu) * rstd * gnv[j] * (gt[j] * sigmoidf(gt[j]));
;       store_bf4(cx.mixed + tokrow * DM + 704 + h * 64 + dv, r);
	v_mov_b32_e32 v24, v202
	v_mov_b32_e32 v25, v203
	v_mov_b32_e32 v0, v210
	v_mov_b32_e32 v1, v211
	v_mov_b32_e32 v2, v212
	v_mov_b32_e32 v3, v213
	v_mul_f32_e32 v18, v18, v16
	v_mul_f32_e32 v22, v22, v16
	v_mul_f32_e32 v14, v14, v16
	v_mul_f32_e32 v6, v6, v16
	v_lshlrev_b32_e32 v23, 16, v24
	v_mul_f32_e32 v0, v0, v18
	v_mul_f32_e32 v18, 0xbfb8aa3b, v23
	v_exp_f32_e32 v18, v18
	v_and_b32_e32 v24, 0xffff0000, v24
	v_lshlrev_b32_e32 v26, 16, v25
	v_and_b32_e32 v25, 0xffff0000, v25
	v_add_f32_e32 v18, 1.0, v18
	v_div_scale_f32 v27, s[96:97], v18, v18, 1.0
	v_rcp_f32_e32 v28, v27
	s_nop 0
	v_fma_f32 v29, -v27, v28, 1.0
	v_fmac_f32_e32 v28, v29, v28
	v_div_scale_f32 v29, vcc, 1.0, v18, 1.0
	v_mul_f32_e32 v30, v29, v28
	v_fma_f32 v31, -v27, v30, v29
	v_fmac_f32_e32 v30, v31, v28
	v_fma_f32 v27, -v27, v30, v29
	v_div_fmas_f32 v27, v27, v28, v30
	v_div_fixup_f32 v18, v27, v18, 1.0
	v_mul_f32_e32 v18, v18, v23
	v_mul_f32_e32 v18, v18, v0
	v_mul_f32_e32 v0, v19, v16
	v_mul_f32_e32 v0, v1, v0
	v_mul_f32_e32 v1, 0xbfb8aa3b, v24
	v_exp_f32_e32 v1, v1
	s_nop 0
	v_add_f32_e32 v1, 1.0, v1
	v_div_scale_f32 v19, s[96:97], v1, v1, 1.0
	v_rcp_f32_e32 v23, v19
	s_nop 0
	v_fma_f32 v27, -v19, v23, 1.0
	v_fmac_f32_e32 v23, v27, v23
	v_div_scale_f32 v27, vcc, 1.0, v1, 1.0
	v_mul_f32_e32 v28, v27, v23
	v_fma_f32 v29, -v19, v28, v27
	v_fmac_f32_e32 v28, v29, v23
	v_fma_f32 v19, -v19, v28, v27
	v_div_fmas_f32 v19, v19, v23, v28
	v_div_fixup_f32 v1, v19, v1, 1.0
	v_mul_f32_e32 v1, v1, v24
	v_mul_f32_e32 v19, v1, v0
	v_mul_f32_e32 v1, 0xbfb8aa3b, v26
	v_exp_f32_e32 v1, v1
	v_mul_f32_e32 v0, v8, v16
	v_mul_f32_e32 v0, v2, v0
	v_add_f32_e32 v1, 1.0, v1
	v_div_scale_f32 v2, s[96:97], v1, v1, 1.0
	v_rcp_f32_e32 v8, v2
	s_nop 0
	v_fma_f32 v23, -v2, v8, 1.0
	v_fmac_f32_e32 v8, v23, v8
	v_div_scale_f32 v23, vcc, 1.0, v1, 1.0
	v_mul_f32_e32 v24, v23, v8
	v_fma_f32 v27, -v2, v24, v23
	v_fmac_f32_e32 v24, v27, v8
	v_fma_f32 v2, -v2, v24, v23
	v_div_fmas_f32 v2, v2, v8, v24
	v_div_fixup_f32 v1, v2, v1, 1.0
	v_mul_f32_e32 v1, v1, v26
	v_mul_f32_e32 v23, v1, v0
	v_mul_f32_e32 v1, 0xbfb8aa3b, v25
	v_exp_f32_e32 v1, v1
	v_mul_f32_e32 v0, v9, v16
	v_mul_f32_e32 v0, v3, v0
	v_add_f32_e32 v1, 1.0, v1
	v_div_scale_f32 v2, s[96:97], v1, v1, 1.0
	v_rcp_f32_e32 v3, v2
	s_nop 0
	v_fma_f32 v8, -v2, v3, 1.0
	v_fmac_f32_e32 v3, v8, v3
	v_div_scale_f32 v8, vcc, 1.0, v1, 1.0
	v_mul_f32_e32 v9, v8, v3
	v_fma_f32 v24, -v2, v9, v8
	v_fmac_f32_e32 v9, v24, v3
	v_fma_f32 v2, -v2, v9, v8
	v_div_fmas_f32 v2, v2, v3, v9
	v_div_fixup_f32 v1, v2, v1, 1.0
	v_mul_f32_e32 v1, v1, v25
	v_lshl_add_u64 v[8:9], s[86:87], 0, v[20:21]
	v_mul_f32_e32 v3, v1, v0
	v_lshl_add_u64 v[0:1], v[8:9], 0, v[128:129]
	v_cvt_pk_bf16_f32 v2, v18, v19
	v_cvt_pk_bf16_f32 v3, v23, v3
	global_store_dwordx2 v[0:1], v[2:3], off offset:1408
	v_lshl_add_u64 v[0:1], v[148:149], 0, v[136:137]
	s_waitcnt vmcnt(5)
	v_mov_b32_e32 v18, v204
	v_mov_b32_e32 v19, v205
	v_mov_b32_e32 v0, v214
	v_mov_b32_e32 v1, v215
	v_mov_b32_e32 v2, v216
	v_mov_b32_e32 v3, v217
	v_lshlrev_b32_e32 v20, 16, v18
	v_mul_f32_e32 v0, v0, v22
	v_mul_f32_e32 v22, 0xbfb8aa3b, v20
	v_exp_f32_e32 v22, v22
	v_and_b32_e32 v18, 0xffff0000, v18
	v_lshlrev_b32_e32 v21, 16, v19
	v_and_b32_e32 v19, 0xffff0000, v19
	v_add_f32_e32 v22, 1.0, v22
	v_div_scale_f32 v23, s[96:97], v22, v22, 1.0
	v_rcp_f32_e32 v24, v23
	s_nop 0
	v_fma_f32 v25, -v23, v24, 1.0
	v_fmac_f32_e32 v24, v25, v24
	v_div_scale_f32 v25, vcc, 1.0, v22, 1.0
	v_mul_f32_e32 v26, v25, v24
	v_fma_f32 v27, -v23, v26, v25
	v_fmac_f32_e32 v26, v27, v24
	v_fma_f32 v23, -v23, v26, v25
	v_div_fmas_f32 v23, v23, v24, v26
	v_div_fixup_f32 v22, v23, v22, 1.0
	v_mul_f32_e32 v20, v22, v20
	v_mul_f32_e32 v20, v20, v0
	v_mul_f32_e32 v0, v17, v16
	v_mul_f32_e32 v0, v1, v0
	v_mul_f32_e32 v1, 0xbfb8aa3b, v18
	v_exp_f32_e32 v1, v1
	s_nop 0
	v_add_f32_e32 v1, 1.0, v1
	v_div_scale_f32 v17, s[96:97], v1, v1, 1.0
	v_rcp_f32_e32 v22, v17
	s_nop 0
	v_fma_f32 v23, -v17, v22, 1.0
	v_fmac_f32_e32 v22, v23, v22
	v_div_scale_f32 v23, vcc, 1.0, v1, 1.0
	v_mul_f32_e32 v24, v23, v22
	v_fma_f32 v25, -v17, v24, v23
	v_fmac_f32_e32 v24, v25, v22
	v_fma_f32 v17, -v17, v24, v23
	v_div_fmas_f32 v17, v17, v22, v24
	v_div_fixup_f32 v1, v17, v1, 1.0
	v_mul_f32_e32 v1, v1, v18
	v_mul_f32_e32 v17, v1, v0
	v_mul_f32_e32 v1, 0xbfb8aa3b, v21
	v_exp_f32_e32 v1, v1
	v_mul_f32_e32 v0, v10, v16
	v_mul_f32_e32 v0, v2, v0
	v_add_f32_e32 v1, 1.0, v1
	v_div_scale_f32 v2, s[96:97], v1, v1, 1.0
	v_rcp_f32_e32 v10, v2
	s_nop 0
	v_fma_f32 v18, -v2, v10, 1.0
	v_fmac_f32_e32 v10, v18, v10
	v_div_scale_f32 v18, vcc, 1.0, v1, 1.0
	v_mul_f32_e32 v22, v18, v10
	v_fma_f32 v23, -v2, v22, v18
	v_fmac_f32_e32 v22, v23, v10
	v_fma_f32 v2, -v2, v22, v18
	v_div_fmas_f32 v2, v2, v10, v22
	v_div_fixup_f32 v1, v2, v1, 1.0
	v_mul_f32_e32 v1, v1, v21
	v_mul_f32_e32 v10, v1, v0
	v_mul_f32_e32 v1, 0xbfb8aa3b, v19
	v_exp_f32_e32 v1, v1
	v_mul_f32_e32 v0, v11, v16
	v_mul_f32_e32 v0, v3, v0
	v_add_f32_e32 v1, 1.0, v1
	v_div_scale_f32 v2, s[96:97], v1, v1, 1.0
	v_rcp_f32_e32 v3, v2
	s_nop 0
	v_fma_f32 v11, -v2, v3, 1.0
	v_fmac_f32_e32 v3, v11, v3
	v_div_scale_f32 v11, vcc, 1.0, v1, 1.0
	v_mul_f32_e32 v18, v11, v3
	v_fma_f32 v21, -v2, v18, v11
	v_fmac_f32_e32 v18, v21, v3
	v_fma_f32 v2, -v2, v18, v11
	v_div_fmas_f32 v2, v2, v3, v18
	v_div_fixup_f32 v1, v2, v1, 1.0
	v_mul_f32_e32 v1, v1, v19
	v_mul_f32_e32 v3, v1, v0
	v_lshl_add_u64 v[0:1], v[8:9], 0, v[136:137]
	v_cvt_pk_bf16_f32 v2, v20, v17
	v_cvt_pk_bf16_f32 v3, v10, v3
	global_store_dwordx2 v[0:1], v[2:3], off offset:1408
	v_lshl_add_u64 v[0:1], v[148:149], 0, v[138:139]
	s_waitcnt vmcnt(4)
; DEVI void store_bf4(bf16_t* p, f32x4 v) { u32x2 w; w.x = pk2(v[0], v[1]); w.y = pk2(v[2], v[3]); *(u32x2*)p = w; }
; DEVI float sigmoidf(float x) { return 1.f / (1.f + __expf(-x)); }
; DEVI void ret_item(const Ctx& cx, const float* __restrict__ gn, const float* __restrict__ xfl, const float* __restrict__ g1, const float* __restrict__ winl, int b, int h, unsigned char* lds, int wv) {
;     ...
;     for (int dvt = 0; dvt < 4; ++dvt) {
;       const int dv = dvt * 16 + quad * 4;
;       const u32x2 gw = *(const u32x2*)(cx.proj + tokrow * PS + C_RG + h * 64 + dv);
;       const float4 gg = *(const float4*)(gn + h * 64 + dv);
;       float gt[4] = {__uint_as_float(gw.x << 16), __uint_as_float(gw.x & 0xffff0000u), __uint_as_float(gw.y << 16), __uint_as_float(gw.y & 0xffff0000u)};
;       float gnv[4] = {gg.x, gg.y, gg.z, gg.w};
;       f32x4 r;
; #pragma unroll
;       for (int j = 0; j < 4; ++j) r[j] = (o[dvt][j] - mu) * rstd * gnv[j] * (gt[j] * sigmoidf(gt[j]));
;       store_bf4(cx.mixed + tokrow * DM + 704 + h * 64 + dv, r);
	v_mov_b32_e32 v10, v206
	v_mov_b32_e32 v11, v207
	v_mov_b32_e32 v0, v218
	v_mov_b32_e32 v1, v219
	v_mov_b32_e32 v2, v220
	v_mov_b32_e32 v3, v221
	v_lshlrev_b32_e32 v17, 16, v10
	v_mul_f32_e32 v0, v0, v14
	v_mul_f32_e32 v14, 0xbfb8aa3b, v17
	v_exp_f32_e32 v14, v14
	v_and_b32_e32 v10, 0xffff0000, v10
	v_lshlrev_b32_e32 v18, 16, v11
	v_and_b32_e32 v11, 0xffff0000, v11
	v_add_f32_e32 v14, 1.0, v14
	v_div_scale_f32 v19, s[96:97], v14, v14, 1.0
	v_rcp_f32_e32 v20, v19
	s_nop 0
	v_fma_f32 v21, -v19, v20, 1.0
	v_fmac_f32_e32 v20, v21, v20
	v_div_scale_f32 v21, vcc, 1.0, v14, 1.0
	v_mul_f32_e32 v22, v21, v20
	v_fma_f32 v23, -v19, v22, v21
	v_fmac_f32_e32 v22, v23, v20
	v_fma_f32 v19, -v19, v22, v21
	v_div_fmas_f32 v19, v19, v20, v22
	v_div_fixup_f32 v14, v19, v14, 1.0
	v_mul_f32_e32 v14, v14, v17
	v_mul_f32_e32 v14, v14, v0
	v_mul_f32_e32 v0, v15, v16
	v_mul_f32_e32 v0, v1, v0
	v_mul_f32_e32 v1, 0xbfb8aa3b, v10
	v_exp_f32_e32 v1, v1
	s_nop 0
	v_add_f32_e32 v1, 1.0, v1
	v_div_scale_f32 v15, s[96:97], v1, v1, 1.0
	v_rcp_f32_e32 v17, v15
	s_nop 0
	v_fma_f32 v19, -v15, v17, 1.0
	v_fmac_f32_e32 v17, v19, v17
	v_div_scale_f32 v19, vcc, 1.0, v1, 1.0
	v_mul_f32_e32 v20, v19, v17
	v_fma_f32 v21, -v15, v20, v19
	v_fmac_f32_e32 v20, v21, v17
	v_fma_f32 v15, -v15, v20, v19
	v_div_fmas_f32 v15, v15, v17, v20
	v_div_fixup_f32 v1, v15, v1, 1.0
	v_mul_f32_e32 v1, v1, v10
	v_mul_f32_e32 v10, v1, v0
	v_mul_f32_e32 v1, 0xbfb8aa3b, v18
	v_exp_f32_e32 v1, v1
	v_mul_f32_e32 v0, v12, v16
	v_mul_f32_e32 v0, v2, v0
	v_add_f32_e32 v1, 1.0, v1
	v_div_scale_f32 v2, s[96:97], v1, v1, 1.0
	v_rcp_f32_e32 v12, v2
	s_nop 0
	v_fma_f32 v15, -v2, v12, 1.0
	v_fmac_f32_e32 v12, v15, v12
	v_div_scale_f32 v15, vcc, 1.0, v1, 1.0
	v_mul_f32_e32 v17, v15, v12
	v_fma_f32 v19, -v2, v17, v15
	v_fmac_f32_e32 v17, v19, v12
	v_fma_f32 v2, -v2, v17, v15
	v_div_fmas_f32 v2, v2, v12, v17
	v_div_fixup_f32 v1, v2, v1, 1.0
	v_mul_f32_e32 v1, v1, v18
	v_mul_f32_e32 v12, v1, v0
	v_mul_f32_e32 v1, 0xbfb8aa3b, v11
	v_exp_f32_e32 v1, v1
	v_mul_f32_e32 v0, v13, v16
	v_mul_f32_e32 v0, v3, v0
	v_add_f32_e32 v1, 1.0, v1
	v_div_scale_f32 v2, s[96:97], v1, v1, 1.0
	v_rcp_f32_e32 v3, v2
	s_nop 0
	v_fma_f32 v13, -v2, v3, 1.0
	v_fmac_f32_e32 v3, v13, v3
	v_div_scale_f32 v13, vcc, 1.0, v1, 1.0
	v_mul_f32_e32 v15, v13, v3
	v_fma_f32 v17, -v2, v15, v13
	v_fmac_f32_e32 v15, v17, v3
	v_fma_f32 v2, -v2, v15, v13
	v_div_fmas_f32 v2, v2, v3, v15
	v_div_fixup_f32 v1, v2, v1, 1.0
	v_mul_f32_e32 v1, v1, v11
	v_mul_f32_e32 v3, v1, v0
	v_lshl_add_u64 v[0:1], v[8:9], 0, v[138:139]
	v_cvt_pk_bf16_f32 v2, v14, v10
	v_cvt_pk_bf16_f32 v3, v12, v3
	global_store_dwordx2 v[0:1], v[2:3], off offset:1408
	v_lshl_add_u64 v[0:1], v[148:149], 0, v[140:141]
	s_waitcnt vmcnt(3)
	v_mov_b32_e32 v10, v208
	v_mov_b32_e32 v11, v209
	v_mov_b32_e32 v0, v172
	v_mov_b32_e32 v1, v173
	v_mov_b32_e32 v2, v174
	v_mov_b32_e32 v3, v175
	v_lshlrev_b32_e32 v12, 16, v10
	v_mul_f32_e32 v0, v0, v6
	v_mul_f32_e32 v6, 0xbfb8aa3b, v12
	v_exp_f32_e32 v6, v6
	v_and_b32_e32 v10, 0xffff0000, v10
	v_lshlrev_b32_e32 v13, 16, v11
	v_and_b32_e32 v11, 0xffff0000, v11
	v_add_f32_e32 v6, 1.0, v6
	v_div_scale_f32 v14, s[96:97], v6, v6, 1.0
	v_rcp_f32_e32 v15, v14
	s_nop 0
	v_fma_f32 v17, -v14, v15, 1.0
	v_fmac_f32_e32 v15, v17, v15
	v_div_scale_f32 v17, vcc, 1.0, v6, 1.0
	v_mul_f32_e32 v18, v17, v15
	v_fma_f32 v19, -v14, v18, v17
	v_fmac_f32_e32 v18, v19, v15
	v_fma_f32 v14, -v14, v18, v17
	v_div_fmas_f32 v14, v14, v15, v18
	v_div_fixup_f32 v6, v14, v6, 1.0
	v_mul_f32_e32 v6, v6, v12
	v_mul_f32_e32 v6, v0, v6
	v_mul_f32_e32 v0, v7, v16
	v_mul_f32_e32 v0, v1, v0
	v_mul_f32_e32 v1, 0xbfb8aa3b, v10
	v_exp_f32_e32 v1, v1
	s_nop 0
	v_add_f32_e32 v1, 1.0, v1
	v_div_scale_f32 v7, s[96:97], v1, v1, 1.0
	v_rcp_f32_e32 v12, v7
	s_nop 0
	v_fma_f32 v14, -v7, v12, 1.0
	v_fmac_f32_e32 v12, v14, v12
	v_div_scale_f32 v14, vcc, 1.0, v1, 1.0
	v_mul_f32_e32 v15, v14, v12
	v_fma_f32 v17, -v7, v15, v14
	v_fmac_f32_e32 v15, v17, v12
	v_fma_f32 v7, -v7, v15, v14
	v_div_fmas_f32 v7, v7, v12, v15
	v_div_fixup_f32 v1, v7, v1, 1.0
	v_mul_f32_e32 v1, v1, v10
	v_mul_f32_e32 v7, v0, v1
	v_mul_f32_e32 v1, 0xbfb8aa3b, v13
	v_exp_f32_e32 v1, v1
	v_mul_f32_e32 v0, v4, v16
	v_mul_f32_e32 v0, v2, v0
	v_add_f32_e32 v1, 1.0, v1
	v_div_scale_f32 v2, s[96:97], v1, v1, 1.0
	v_rcp_f32_e32 v4, v2
	s_nop 0
	v_fma_f32 v10, -v2, v4, 1.0
	v_fmac_f32_e32 v4, v10, v4
	v_div_scale_f32 v10, vcc, 1.0, v1, 1.0
	v_mul_f32_e32 v12, v10, v4
	v_fma_f32 v14, -v2, v12, v10
	v_fmac_f32_e32 v12, v14, v4
	v_fma_f32 v2, -v2, v12, v10
	v_div_fmas_f32 v2, v2, v4, v12
	v_div_fixup_f32 v1, v2, v1, 1.0
	v_mul_f32_e32 v1, v1, v13
	v_mul_f32_e32 v4, v0, v1
	v_mul_f32_e32 v1, 0xbfb8aa3b, v11
	v_exp_f32_e32 v1, v1
	v_mul_f32_e32 v0, v5, v16
	v_mul_f32_e32 v0, v0, v3
	v_add_f32_e32 v1, 1.0, v1
	v_div_scale_f32 v2, s[96:97], v1, v1, 1.0
	v_rcp_f32_e32 v3, v2
	s_mov_b64 s[96:97], 0x100
	v_lshl_add_u64 v[124:125], v[124:125], 0, s[96:97]
	v_lshl_add_u64 v[126:127], v[126:127], 0, s[96:97]
	v_fma_f32 v5, -v2, v3, 1.0
	v_fmac_f32_e32 v3, v5, v3
	v_div_scale_f32 v5, vcc, 1.0, v1, 1.0
	v_mul_f32_e32 v10, v5, v3
	v_fma_f32 v12, -v2, v10, v5
	v_fmac_f32_e32 v10, v12, v3
	v_fma_f32 v2, -v2, v10, v5
	v_div_fmas_f32 v2, v2, v3, v10
	v_div_fixup_f32 v1, v2, v1, 1.0
	v_mul_f32_e32 v1, v1, v11
	v_mul_f32_e32 v3, v0, v1
	v_lshl_add_u64 v[0:1], v[8:9], 0, v[140:141]
	v_cvt_pk_bf16_f32 v2, v6, v7
	v_cvt_pk_bf16_f32 v3, v4, v3
	global_store_dwordx2 v[0:1], v[2:3], off offset:1408
	s_cbranch_scc0 .LBB0_1344
; DEVI bf16_t f2bf(float f) { return (bf16_t)(pk2(f, 0.f) & 0xffffu); }
; DEVI float fexp2(float x) { return __builtin_amdgcn_exp2f(x); }
; DEVI void ret_item(const Ctx& cx, const float* __restrict__ gn, const float* __restrict__ xfl, const float* __restrict__ g1, const float* __restrict__ winl, int b, int h, unsigned char* lds, int wv) {
;     ...
;   for (int ci = 0; ci < 16; ++ci) {
;     const int s0 = ci * 128;
;     u32x4 kr[2], vr[2];
; #pragma unroll
;     for (int r = 0; r < 2; ++r) {
;       kr[r] = *(const u32x4*)(cx.proj + ((size_t)(b * S + s0 + lr + 64 * r)) * PS + C_RK + h * 64 + lc * 8);
;       vr[r] = *(const u32x4*)(cx.retvT + ((size_t)((b * 5 + h) * 64 + vrw + 32 * r)) * S + s0 + vc * 8);
;     }
;     const size_t tokrow = (size_t)(b * S + s0 + i);
;     bf16x8 q[2];
; #pragma unroll
;     for (int ks = 0; ks < 2; ++ks) q[ks] = *(const bf16x8*)(cx.proj + tokrow * PS + C_RQ + h * 64 + ks * 32 + quad * 8);
;     __syncthreads();
; #pragma unroll
;     for (int t = 0; t < 2; ++t)
; #pragma unroll
;       for (int j = 0; j < 4; ++j)
;         *(bf16_t*)(lds + RET_ST + (et * 16 + quad * 4 + j) * LDS_ROW + ((dt0 + t) * 16 + idx) * 2) = f2bf(st[t][j]);
; #pragma unroll
;     for (int r = 0; r < 2; ++r) {
;       const int row = lr + 64 * r;
;       *(u32x4*)(lds + RET_KS + row * LDS_ROW + lc * 16) = kr[r];
;       const float wd = fexp2((float)(127 - row) * lg);
; #pragma unroll
;       for (int e = 0; e < 4; ++e) {
;         unsigned w = kr[r][e];
;         float lo = __uint_as_float(w << 16) * wd, hi = __uint_as_float(w & 0xffff0000u) * wd;
;         *(bf16_t*)(lds + RET_KWT + (lc * 8 + 2 * e) * RET_ROWT + row * 2) = f2bf(lo);
;         *(bf16_t*)(lds + RET_KWT + (lc * 8 + 2 * e + 1) * RET_ROWT + row * 2) = f2bf(hi);
;       }
;       *(u32x4*)(lds + RET_VT + (vrw + 32 * r) * RET_ROWT + vc * 16) = vr[r];
;     }
;     __syncthreads();
.LBB0_1296:
	s_movk_i32 s3, 0x1200
	v_add_u32_e32 v150, s2, v158
	v_mov_b64_e32 v[16:17], s[84:85]
	v_mad_i64_i32 v[148:149], vcc, v150, s3, v[16:17]
	s_waitcnt vmcnt(4)
	v_mov_b32_e32 v12, v178
	v_mov_b32_e32 v13, v179
	v_mov_b32_e32 v14, v180
	v_mov_b32_e32 v15, v181
	v_mov_b32_e32 v8, v182
	v_mov_b32_e32 v9, v183
	v_mov_b32_e32 v10, v184
	v_mov_b32_e32 v11, v185
	v_mov_b32_e32 v4, v186
	v_mov_b32_e32 v5, v187
	v_mov_b32_e32 v6, v188
	v_mov_b32_e32 v7, v189
	v_mov_b32_e32 v0, v190
	v_mov_b32_e32 v1, v191
	v_mov_b32_e32 v2, v192
	v_mov_b32_e32 v3, v193
	v_mov_b32_e32 v38, v194
	v_mov_b32_e32 v39, v195
	v_mov_b32_e32 v40, v196
	v_mov_b32_e32 v41, v197
	v_mov_b32_e32 v34, v198
	v_mov_b32_e32 v35, v199
	v_mov_b32_e32 v36, v200
	v_mov_b32_e32 v37, v201
	v_cvt_pk_bf16_f32 v16, v74, v33
	s_waitcnt vmcnt(63) expcnt(7) lgkmcnt(15)
	s_barrier
	ds_write_b16 v160, v16 offset:53248
	v_cvt_pk_bf16_f32 v16, v75, v33
	ds_write_b16 v160, v16 offset:53392
	v_cvt_pk_bf16_f32 v16, v142, v33
	ds_write_b16 v160, v16 offset:53536
	v_cvt_pk_bf16_f32 v16, v143, v33
	ds_write_b16 v160, v16 offset:53680
	v_cvt_pk_bf16_f32 v16, v144, v33
	ds_write_b16 v161, v16 offset:53248
	v_cvt_pk_bf16_f32 v16, v145, v33
	ds_write_b16 v161, v16 offset:53392
	v_cvt_pk_bf16_f32 v16, v146, v33
	ds_write_b16 v161, v16 offset:53536
	v_cvt_pk_bf16_f32 v16, v147, v33
	v_add_u32_e32 v17, v154, v153
	s_movk_i32 s33, 0x1200
	ds_write_b16 v161, v16 offset:53680
	ds_write_b128 v162, v[12:15]
	v_lshlrev_b32_e32 v16, 16, v12
	v_and_b32_e32 v12, 0xffff0000, v12
	v_mul_f32_e32 v12, v152, v12
	v_cvt_pk_bf16_f32 v12, v12, v33
	ds_write_b16 v17, v12 offset:18704
	v_lshlrev_b32_e32 v12, 16, v13
	v_mul_f32_e32 v12, v152, v12
	v_and_b32_e32 v13, 0xffff0000, v13
	v_cvt_pk_bf16_f32 v12, v12, v33
	v_mul_f32_e32 v13, v152, v13
	ds_write_b16 v17, v12 offset:18976
	v_cvt_pk_bf16_f32 v12, v13, v33
	ds_write_b16 v17, v12 offset:19248
	v_lshlrev_b32_e32 v12, 16, v14
	v_mul_f32_e32 v12, v152, v12
	v_and_b32_e32 v13, 0xffff0000, v14
	v_cvt_pk_bf16_f32 v12, v12, v33
	v_mul_f32_e32 v13, v152, v13
	ds_write_b16 v17, v12 offset:19520
	v_cvt_pk_bf16_f32 v12, v13, v33
	ds_write_b16 v17, v12 offset:19792
	v_lshlrev_b32_e32 v12, 16, v15
	v_mul_f32_e32 v12, v152, v12
	v_and_b32_e32 v13, 0xffff0000, v15
	v_cvt_pk_bf16_f32 v12, v12, v33
	v_mul_f32_e32 v16, v152, v16
	v_mul_f32_e32 v13, v152, v13
	ds_write_b16 v17, v12 offset:20064
	v_cvt_pk_bf16_f32 v12, v13, v33
	v_cvt_pk_bf16_f32 v16, v16, v33
	ds_write_b16 v17, v16 offset:18432
	ds_write_b16 v17, v12 offset:20336
	ds_write_b128 v163, v[8:11] offset:35840
	ds_write_b128 v162, v[4:7] offset:9216
	v_lshlrev_b32_e32 v8, 16, v4
	v_and_b32_e32 v4, 0xffff0000, v4
	v_mul_f32_e32 v4, v155, v4
	v_cvt_pk_bf16_f32 v4, v4, v33
	ds_write_b16 v164, v4 offset:18704
	v_lshlrev_b32_e32 v4, 16, v5
	v_mul_f32_e32 v4, v155, v4
	v_and_b32_e32 v5, 0xffff0000, v5
	v_cvt_pk_bf16_f32 v4, v4, v33
	v_mul_f32_e32 v5, v155, v5
	ds_write_b16 v164, v4 offset:18976
	v_cvt_pk_bf16_f32 v4, v5, v33
	ds_write_b16 v164, v4 offset:19248
	v_lshlrev_b32_e32 v4, 16, v6
	v_mul_f32_e32 v4, v155, v4
	v_and_b32_e32 v5, 0xffff0000, v6
	v_cvt_pk_bf16_f32 v4, v4, v33
	v_mul_f32_e32 v5, v155, v5
	ds_write_b16 v164, v4 offset:19520
	v_cvt_pk_bf16_f32 v4, v5, v33
	ds_write_b16 v164, v4 offset:19792
	v_lshlrev_b32_e32 v4, 16, v7
	v_mul_f32_e32 v4, v155, v4
	v_and_b32_e32 v5, 0xffff0000, v7
	v_cvt_pk_bf16_f32 v4, v4, v33
	v_mul_f32_e32 v8, v155, v8
	v_mul_f32_e32 v5, v155, v5
	ds_write_b16 v164, v4 offset:20064
	v_cvt_pk_bf16_f32 v4, v5, v33
	v_cvt_pk_bf16_f32 v8, v8, v33
	ds_write_b16 v164, v8 offset:18432
	ds_write_b16 v164, v4 offset:20336
	ds_write_b128 v163, v[0:3] offset:44544
	v_mov_b32_e32 v1, 0
	v_mov_b32_e32 v2, 0
	v_mov_b32_e32 v3, 0
	v_mov_b32_e32 v4, 0
	s_waitcnt lgkmcnt(0)
	s_barrier
	s_cmpk_eq_i32 s2, 0x780
	s_cbranch_scc1 .Lret_nopf
	v_add_u32_e32 v202, s2, v159
	v_add_u32_e32 v202, 0x80, v202
	v_mul_u32_u24_e32 v202, 0x1200, v202
	v_add_co_u32_e32 v204, vcc, v122, v202
	v_addc_co_u32_e32 v205, vcc, 0, v123, vcc
	global_load_dwordx4 v[178:181], v[204:205], off offset:3328
	global_load_dwordx4 v[182:185], v[124:125], off offset:256
	v_add_co_u32_e32 v206, vcc, 0x48000, v204
	v_addc_co_u32_e32 v207, vcc, 0, v205, vcc
	global_load_dwordx4 v[186:189], v[206:207], off offset:3328
	global_load_dwordx4 v[190:193], v[126:127], off offset:256
	v_add_co_u32_e32 v208, vcc, 0x90000, v148
	v_addc_co_u32_e32 v209, vcc, 0, v149, vcc
	v_add_co_u32_e32 v208, vcc, v208, v32
	v_addc_co_u32_e32 v209, vcc, 0, v209, vcc
	global_load_dwordx4 v[194:197], v[208:209], off offset:2688
	global_load_dwordx4 v[198:201], v[208:209], off offset:2752
.Lret_nopf:
	v_add_co_u32_e32 v202, vcc, v148, v128
	v_addc_co_u32_e32 v203, vcc, 0, v149, vcc
	global_load_dwordx2 v[202:203], v[202:203], off offset:3968
	global_load_dwordx4 v[210:213], v[110:111], off
	v_add_co_u32_e32 v204, vcc, v148, v136
	v_addc_co_u32_e32 v205, vcc, 0, v149, vcc
	global_load_dwordx2 v[204:205], v[204:205], off offset:3968
	global_load_dwordx4 v[214:217], v[112:113], off
	v_add_co_u32_e32 v206, vcc, v148, v138
	v_addc_co_u32_e32 v207, vcc, 0, v149, vcc
	global_load_dwordx2 v[206:207], v[206:207], off offset:3968
	global_load_dwordx4 v[218:221], v[114:115], off
	v_add_co_u32_e32 v208, vcc, v148, v140
	v_addc_co_u32_e32 v209, vcc, 0, v149, vcc
	global_load_dwordx2 v[208:209], v[208:209], off offset:3968
	global_load_dwordx4 v[172:175], v[116:117], off
	s_and_saveexec_b64 vcc, s[0:1]
	s_cbranch_execz .LBB0_1298
	ds_read_b128 v[0:3], v168
	ds_read_b128 v[4:7], v168 offset:64
	s_waitcnt lgkmcnt(1)
	v_mfma_f32_16x16x32_bf16 v[0:3], v[0:3], v[38:41], 0
	s_waitcnt lgkmcnt(0)
	v_mfma_f32_16x16x32_bf16 v[0:3], v[4:7], v[34:37], v[0:3]
	s_nop 7
	v_mul_f32_e32 v0, v156, v0
	v_mul_f32_e32 v6, v157, v1
	v_pk_mul_f32 v[4:5], v[84:85], v[2:3]
	v_cndmask_b32_e64 v1, v0, 0, s[4:5]
	v_cndmask_b32_e64 v2, 0, v6, s[6:7]
	v_cndmask_b32_e64 v3, v4, 0, s[10:11]
	v_cndmask_b32_e64 v4, v5, 0, s[8:9]
; DEVI unsigned pk2(float lo, float hi) { unsigned r; asm("v_cvt_pk_bf16_f32 %0, %1, %2" : "=v"(r) : "v"(lo), "v"(hi)); return r; }
; DEVI f32x4 mfma16(bf16x8 a, bf16x8 b, f32x4 c) { return __builtin_amdgcn_mfma_f32_16x16x32_bf16(a, b, c, 0, 0, 0); }
; DEVI float fexp2(float x) { return __builtin_amdgcn_exp2f(x); }
; DEVI void ret_item(const Ctx& cx, const float* __restrict__ gn, const float* __restrict__ xfl, const float* __restrict__ g1, const float* __restrict__ winl, int b, int h, unsigned char* lds, int wv) {
;     ...
; #pragma unroll
;     for (int kc = 0; kc < 4; ++kc) {
;       f32x4 s2[2];
; #pragma unroll
;       for (int u = 0; u < 2; ++u) {
;         const int kt = 2 * kc + u;
;         s2[u] = (f32x4){0.f, 0.f, 0.f, 0.f};
;         if (kt <= wave) {
; #pragma unroll
;           for (int ks = 0; ks < 2; ++ks) {
;             bf16x8 kf = *(const bf16x8*)(lds + RET_KS + (kt * 16 + idx) * LDS_ROW + ks * 64 + quad * 16);
;             s2[u] = mfma16(kf, q[ks], s2[u]);
;           }
; #pragma unroll
;           for (int j = 0; j < 4; ++j) { const int key = kt * 16 + quad * 4 + j; s2[u][j] = (key <= i) ? s2[u][j] * fexp2((float)(i - key) * lg) : 0.f; }
;         }
;       }
;       pb[kc] = as_bf8((u32x4){pk2(s2[0][0], s2[0][1]), pk2(s2[0][2], s2[0][3]), pk2(s2[1][0], s2[1][1]), pk2(s2[1][2], s2[1][3])});
;     }
.LBB0_1298:
	s_or_b64 exec, exec, vcc
	v_mov_b32_e32 v0, 0
	v_mov_b32_e32 v5, 0
	v_mov_b32_e32 v6, 0
	v_mov_b32_e32 v7, 0
	v_mov_b32_e32 v8, 0
	s_and_saveexec_b64 vcc, s[12:13]
	s_cbranch_execz .LBB0_1300
	ds_read_b128 v[6:9], v168 offset:2304
	ds_read_b128 v[10:13], v168 offset:2368
	s_waitcnt lgkmcnt(1)
	v_mfma_f32_16x16x32_bf16 v[6:9], v[6:9], v[38:41], 0
	s_waitcnt lgkmcnt(0)
	v_mfma_f32_16x16x32_bf16 v[6:9], v[10:13], v[34:37], v[6:9]
	s_nop 7
	v_pk_mul_f32 v[6:7], v[86:87], v[6:7]
	v_pk_mul_f32 v[8:9], v[88:89], v[8:9]
	v_cndmask_b32_e64 v5, v6, 0, s[16:17]
	v_cndmask_b32_e64 v6, v7, 0, s[14:15]
	v_cndmask_b32_e64 v7, v8, 0, s[20:21]
	v_cndmask_b32_e64 v8, v9, 0, s[18:19]
.LBB0_1300:
	s_or_b64 exec, exec, vcc
	v_cvt_pk_bf16_f32 v42, v1, v2
	v_cvt_pk_bf16_f32 v43, v3, v4
	v_mov_b32_e32 v1, 0
	v_mov_b32_e32 v3, 0
	v_mov_b32_e32 v4, 0
	v_cvt_pk_bf16_f32 v44, v5, v6
	v_cvt_pk_bf16_f32 v45, v7, v8
	s_and_saveexec_b64 vcc, s[22:23]
	s_cbranch_execz .LBB0_1302
	ds_read_b128 v[0:3], v168 offset:4608
	ds_read_b128 v[4:7], v168 offset:4672
	s_waitcnt lgkmcnt(1)
	v_mfma_f32_16x16x32_bf16 v[0:3], v[0:3], v[38:41], 0
	s_waitcnt lgkmcnt(0)
	v_mfma_f32_16x16x32_bf16 v[0:3], v[4:7], v[34:37], v[0:3]
	s_nop 7
	v_pk_mul_f32 v[0:1], v[90:91], v[0:1]
	v_pk_mul_f32 v[4:5], v[92:93], v[2:3]
	v_cndmask_b32_e64 v0, v0, 0, s[26:27]
	v_cndmask_b32_e64 v1, v1, 0, s[24:25]
	v_cndmask_b32_e64 v3, v4, 0, s[30:31]
	v_cndmask_b32_e64 v4, v5, 0, s[28:29]
.LBB0_1302:
	s_or_b64 exec, exec, vcc
	v_mov_b32_e32 v2, 0
	v_mov_b32_e32 v5, 0
	v_mov_b32_e32 v6, 0
	v_mov_b32_e32 v7, 0
	v_mov_b32_e32 v8, 0
	s_and_saveexec_b64 vcc, s[34:35]
	s_cbranch_execz .LBB0_1304
	ds_read_b128 v[6:9], v168 offset:6912
	ds_read_b128 v[10:13], v168 offset:6976
	s_waitcnt lgkmcnt(1)
	v_mfma_f32_16x16x32_bf16 v[6:9], v[6:9], v[38:41], 0
	s_waitcnt lgkmcnt(0)
	v_mfma_f32_16x16x32_bf16 v[6:9], v[10:13], v[34:37], v[6:9]
	s_nop 7
	v_pk_mul_f32 v[6:7], v[94:95], v[6:7]
	v_pk_mul_f32 v[8:9], v[96:97], v[8:9]
	v_cndmask_b32_e64 v5, v6, 0, s[38:39]
	v_cndmask_b32_e64 v6, v7, 0, s[36:37]
	v_cndmask_b32_e64 v7, v8, 0, s[42:43]
	v_cndmask_b32_e64 v8, v9, 0, s[40:41]
.LBB0_1304:
	s_or_b64 exec, exec, vcc
	v_cvt_pk_bf16_f32 v46, v0, v1
	v_cvt_pk_bf16_f32 v47, v3, v4
	v_mov_b32_e32 v0, 0
	v_mov_b32_e32 v3, 0
	v_mov_b32_e32 v4, 0
	v_cvt_pk_bf16_f32 v48, v5, v6
	v_cvt_pk_bf16_f32 v49, v7, v8
	s_and_saveexec_b64 vcc, s[44:45]
	s_cbranch_execz .LBB0_1306
	ds_read_b128 v[0:3], v168 offset:9216
	ds_read_b128 v[4:7], v168 offset:9280
	s_waitcnt lgkmcnt(1)
	v_mfma_f32_16x16x32_bf16 v[0:3], v[0:3], v[38:41], 0
	s_waitcnt lgkmcnt(0)
	v_mfma_f32_16x16x32_bf16 v[0:3], v[4:7], v[34:37], v[0:3]
	s_nop 7
	v_pk_mul_f32 v[0:1], v[98:99], v[0:1]
	v_pk_mul_f32 v[4:5], v[100:101], v[2:3]
	v_cndmask_b32_e64 v2, v0, 0, s[48:49]
	v_cndmask_b32_e64 v0, v1, 0, s[46:47]
	v_cndmask_b32_e64 v3, v4, 0, s[52:53]
	v_cndmask_b32_e64 v4, v5, 0, s[50:51]
.LBB0_1306:
	s_or_b64 exec, exec, vcc
	v_mov_b32_e32 v1, 0
	v_mov_b32_e32 v5, 0
	v_mov_b32_e32 v6, 0
	v_mov_b32_e32 v7, 0
	v_mov_b32_e32 v8, 0
	s_and_saveexec_b64 vcc, s[54:55]
	s_cbranch_execz .LBB0_1308
	ds_read_b128 v[6:9], v168 offset:11520
	ds_read_b128 v[10:13], v168 offset:11584
	s_waitcnt lgkmcnt(1)
	v_mfma_f32_16x16x32_bf16 v[6:9], v[6:9], v[38:41], 0
	s_waitcnt lgkmcnt(0)
	v_mfma_f32_16x16x32_bf16 v[6:9], v[10:13], v[34:37], v[6:9]
	s_nop 7
	v_pk_mul_f32 v[6:7], v[102:103], v[6:7]
	v_pk_mul_f32 v[8:9], v[104:105], v[8:9]
	v_cndmask_b32_e64 v5, v6, 0, s[58:59]
	v_cndmask_b32_e64 v6, v7, 0, s[56:57]
	v_cndmask_b32_e64 v7, v8, 0, s[62:63]
	v_cndmask_b32_e64 v8, v9, 0, s[60:61]
.LBB0_1308:
	s_or_b64 exec, exec, vcc
	v_cvt_pk_bf16_f32 v50, v2, v0
	v_cvt_pk_bf16_f32 v51, v3, v4
	v_mov_b32_e32 v2, 0
	v_mov_b32_e32 v3, 0
	v_mov_b32_e32 v4, 0
	v_cvt_pk_bf16_f32 v52, v5, v6
	v_cvt_pk_bf16_f32 v53, v7, v8
	s_and_saveexec_b64 vcc, s[64:65]
	s_cbranch_execz .LBB0_1310
	ds_read_b128 v[0:3], v168 offset:13824
	ds_read_b128 v[4:7], v168 offset:13888
	s_waitcnt lgkmcnt(1)
	v_mfma_f32_16x16x32_bf16 v[0:3], v[0:3], v[38:41], 0
	s_waitcnt lgkmcnt(0)
	v_mfma_f32_16x16x32_bf16 v[0:3], v[4:7], v[34:37], v[0:3]
	s_nop 7
	v_pk_mul_f32 v[4:5], v[106:107], v[0:1]
	v_pk_mul_f32 v[6:7], v[108:109], v[2:3]
	v_cndmask_b32_e64 v1, v4, 0, s[68:69]
	v_cndmask_b32_e64 v2, v5, 0, s[66:67]
	v_cndmask_b32_e64 v3, v6, 0, s[72:73]
	v_cndmask_b32_e64 v4, v7, 0, s[70:71]
.LBB0_1310:
	s_or_b64 exec, exec, vcc
	v_mov_b32_e32 v0, 0
	v_mov_b32_e32 v5, 0
	v_mov_b32_e32 v6, 0
	v_mov_b32_e32 v7, 0
	v_mov_b32_e32 v8, 0
	s_and_saveexec_b64 vcc, s[74:75]
	s_cbranch_execz .LBB0_1312
	ds_read_b128 v[6:9], v168 offset:16128
	ds_read_b128 v[10:13], v168 offset:16192
	s_waitcnt lgkmcnt(1)
	v_mfma_f32_16x16x32_bf16 v[6:9], v[6:9], v[38:41], 0
	s_waitcnt lgkmcnt(0)
	v_mfma_f32_16x16x32_bf16 v[6:9], v[10:13], v[34:37], v[6:9]
	s_nop 7
	v_pk_mul_f32 v[6:7], v[118:119], v[6:7]
	v_pk_mul_f32 v[8:9], v[120:121], v[8:9]
	v_cndmask_b32_e64 v5, v6, 0, s[78:79]
	v_cndmask_b32_e64 v6, v7, 0, s[76:77]
	v_cndmask_b32_e64 v7, v8, 0, s[82:83]
	v_cndmask_b32_e64 v8, v9, 0, s[80:81]

; DEVI f32x4 mfma16(bf16x8 a, bf16x8 b, f32x4 c) { return __builtin_amdgcn_mfma_f32_16x16x32_bf16(a, b, c, 0, 0, 0); }
; DEVI void ret_item(const Ctx& cx, const float* __restrict__ gn, const float* __restrict__ xfl, const float* __restrict__ g1, const float* __restrict__ winl, int b, int h, unsigned char* lds, int wv) {
;     ...
; #pragma unroll
;       for (int ks = 0; ks < 2; ++ks) {
;         bf16x8 sf = *(const bf16x8*)(lds + RET_ST + (dvt * 16 + idx) * LDS_ROW + ks * 64 + quad * 16);
;         oi[dvt] = mfma16(sf, q[ks], oi[dvt]);
;       }
.LBB0_1320:
	s_or_b64 exec, exec, vcc
	ds_read_b128 v[16:19], v168 offset:53248
	ds_read_b128 v[20:23], v168 offset:53312
	v_mov_b32_e32 v62, 0
	v_add_u32_e32 v66, 0x9800, v169
	v_mov_b32_e32 v63, 0
	v_mov_b32_e32 v64, 0
	v_mov_b32_e32 v65, 0
	s_waitcnt lgkmcnt(1)
	v_mfma_f32_16x16x32_bf16 v[16:19], v[16:19], v[38:41], 0
	s_waitcnt lgkmcnt(0)
	v_mfma_f32_16x16x32_bf16 v[58:61], v[20:23], v[34:37], v[16:19]
	s_and_saveexec_b64 vcc, s[0:1]
	s_cbranch_execz .LBB0_1322
	s_nop 3
	ds_read2_b64 v[16:19], v66 offset0:160 offset1:164
	s_waitcnt lgkmcnt(0)
	v_mfma_f32_16x16x32_bf16 v[62:65], v[16:19], v[42:45], 0
